# static s_setprio 1 for waves 4-7 over the whole attention phase (unit loop head + both STEP bodies), reset to 0 before the seam; timing-only
# baseline (speedup 1.0000x reference)
; __global__ void __launch_bounds__(NWAVES * 64, 2) mk_fwd(Args a_unused) {
;     ...
;         for (int u = vcu; u < 3072; u += G) {
;     ...
;             if (u < 2048) { if (ATTM & 1) {
;                 int rowbase, seqL, bh, qb;
;                 if (u < 1024) { bh = u >> 6; qb = u & 63; rowbase = (bh >> 3) * 8192; seqL = 8192; }
;                 else { const int v = u - 1024; bh = v >> 5; qb = v & 31; rowbase = MP + (bh >> 3) * 4096; seqL = 4096; }
;                 att::attn_unit<0>(P0, P1, rowbase, seqL, bh & 7, qb, lam, a.subln_g, a.rel_tab, (char*)lds); }
;             } else if (ATTM & 2) {
;                 int rowbase, seqL, bh, rb;
;                 if (u < 2560) { const int v = u - 2048; bh = v >> 5; rb = v & 31; rowbase = (bh >> 3) * 8192; seqL = 8192; }
;                 else { const int v = u - 2560; bh = v >> 4; rb = v & 15; rowbase = MP + (bh >> 3) * 4096; seqL = 4096; }
.LBB0_161:
	s_add_i32 s33, s33, s24
	s_cmpk_gt_i32 s33, 0xbff
	s_cbranch_scc1 .LBB0_248
.LBB0_162:
	s_cmp_lt_u32 s32, 0x100
	s_cbranch_scc1 .Lprio_u
	s_setprio 1
.Lprio_u:
	s_cmpk_gt_i32 s33, 0x7ff
	s_mov_b64 s[4:5], -1
	s_cbranch_scc0 .LBB0_187
	s_cmpk_gt_u32 s33, 0x9ff
	s_cbranch_scc0 .LBB0_165
	s_add_i32 s4, s33, 0xfffff600
	s_lshr_b32 s34, s4, 4
	s_lshl_b32 s4, s4, 5
	s_and_b32 s4, s4, 0x7ffff000
	s_and_b32 s35, s33, 15
	s_add_i32 s37, s4, 0x4000
	s_mov_b64 s[4:5], 0

; __device__ __forceinline__ unsigned xb_ld(unsigned* p)              { return __hip_atomic_load(p, __ATOMIC_RELAXED, __HIP_MEMORY_SCOPE_AGENT); }
; __device__ __forceinline__ void xcd_barrier_complete(unsigned* bar, unsigned x, unsigned& nloc, unsigned& nx) {
;     const unsigned G = gridDim.x * gridDim.y * gridDim.z;
;     unsigned sum, cnt, mine, sp = 0u;
;     for (;;) {
;         sum = 0u; cnt = 0u; mine = 0u;
; #pragma unroll
;         for (unsigned j = 0; j < 16; ++j) { const unsigned c = xb_ld(&bar[XB_XCNT(j)]); sum += c; cnt += (c > 0u) ? 1u : 0u; mine = (j == x) ? c : mine; }
; __device__ __forceinline__ void xcd_barrier(const XcdBarrier& b) {
;     asm volatile("s_waitcnt vmcnt(0)" ::: "memory");
;     __syncthreads();
;     if (threadIdx.x == 0) {
;         unsigned* bar = b.bar;
;         __builtin_amdgcn_s_waitcnt(0);
;         unsigned nloc = b.st[0], nx = b.st[1];
;         if (nloc == 0u) { xcd_barrier_complete(bar, b.x, nloc, nx); b.st[0] = nloc; b.st[1] = nx; }
.LBB0_248:
	s_setprio 0
	s_mov_b64 s[6:7], s[0:1]
	s_getreg_b32 s8, hwreg(HW_REG_XCC_ID, 0, 4)
	s_waitcnt vmcnt(0)
	s_waitcnt lgkmcnt(0)
	s_barrier
	s_and_saveexec_b64 s[4:5], s[14:15]
	s_cbranch_execz .LBB0_300
	s_add_i32 s9, 0, 0x23ff0
	v_mov_b32_e32 v0, s9
	s_load_dwordx2 s[6:7], s[6:7], 0x98
	s_waitcnt vmcnt(0) expcnt(0) lgkmcnt(0)
	ds_read_b32 v2, v0
	s_add_i32 s9, 0, 0x23ff4
	v_mov_b32_e32 v0, s9
	ds_read_b32 v0, v0
	s_and_b32 s21, s8, 15
	s_waitcnt lgkmcnt(1)
	v_cmp_ne_u32_e32 vcc, 0, v2
	s_cbranch_vccnz .LBB0_264
	s_add_u32 s8, s6, 0x80200
	s_addc_u32 s9, s7, 0
	s_add_u32 s10, s6, 0x80400
	s_addc_u32 s11, s7, 0
	s_add_u32 s12, s6, 0x80500
	s_addc_u32 s13, s7, 0
	s_add_u32 s16, s6, 0x80600
	s_addc_u32 s17, s7, 0
	s_add_u32 s18, s6, 0x80700
	s_addc_u32 s19, s7, 0
	s_add_u32 s28, s6, 0x80800
	s_addc_u32 s29, s7, 0
	s_add_u32 s30, s6, 0x80900
	s_addc_u32 s31, s7, 0
	s_add_u32 s34, s6, 0x80a00
	s_addc_u32 s35, s7, 0
	s_add_u32 s36, s6, 0x80b00
	s_addc_u32 s37, s7, 0
	s_add_u32 s38, s6, 0x80c00
	s_addc_u32 s39, s7, 0
	s_add_u32 s40, s6, 0x80d00
	s_addc_u32 s41, s7, 0
	s_add_u32 s42, s6, 0x80e00
	s_addc_u32 s43, s7, 0
	s_add_u32 s44, s6, 0x80f00
	s_addc_u32 s45, s7, 0
	s_add_u32 s46, s6, 0x81000
	s_addc_u32 s47, s7, 0
	s_add_u32 s48, s6, 0x81100
	s_addc_u32 s49, s7, 0
	s_add_u32 s50, s6, 0x81200
	s_addc_u32 s51, s7, 0
	s_mul_i32 s23, s25, s3
	s_add_u32 s52, s6, 0x81300
	s_mul_i32 s23, s23, s24
	s_addc_u32 s53, s7, 0
	s_mov_b32 s33, 1
	v_mov_b32_e32 v16, 0
	s_branch .LBB0_252
